# SSD scan: intra-chunk score tiles (tile2, j-steps 0,1) computed once per n-half group (4 waves split the work, written in place over the CB image in LDS) instead of by every wave
# speedup vs baseline: 1.0277x; 1.0061x over previous
.LBB0_1648:
	s_or_b64 exec, exec, s[0:1]
	v_readlane_b32 s0, v251, 37
	v_readlane_b32 s1, v251, 38
	s_add_u32 s0, s31, s0
	s_addc_u32 s1, s30, s1
	v_readlane_b32 s4, v253, 16
	s_add_u32 s0, s0, s4
	s_addc_u32 s1, s1, 0
	s_lshl_b32 s4, s9, 1
	v_lshlrev_b32_e32 v115, 2, v3
	s_add_u32 s0, s0, s4
	v_lshlrev_b32_e32 v126, 7, v4
	s_addc_u32 s1, s1, 0
	v_lshlrev_b32_e32 v4, 1, v115
	v_mov_b32_e32 v5, v11
	v_readlane_b32 s4, v250, 8
	v_lshl_add_u64 v[4:5], s[0:1], 0, v[4:5]
	s_mov_b64 s[0:1], 0x48df8000
	s_ashr_i32 s45, s80, 8
	s_lshl_b32 s35, s4, 11
	v_readlane_b32 s5, v253, 63
	v_lshl_add_u64 v[92:93], v[4:5], 0, s[0:1]
	s_lshl_b32 s23, s45, 7
	s_and_b32 s0, s8, 0xfffffc0
	s_add_i32 s1, s5, s35
	s_cmp_gt_i32 s4, 16
	s_cselect_b64 s[82:83], -1, 0
	s_cmp_gt_u32 s4, 33
	s_cselect_b64 s[88:89], -1, 0
	s_lshl_b32 s33, s4, 10
	s_ashr_i32 s81, s33, 31
	s_cmp_gt_i32 s4, 8
	s_cselect_b64 s[90:91], -1, 0
	s_cmp_gt_u32 s12, 33
	s_cselect_b64 s[10:11], -1, 0
	s_lshl_b32 s25, s12, 10
	s_ashr_i32 s93, s25, 31
	v_writelane_b32 v255, s10, 15
	s_cmp_gt_i32 s4, 0
	v_or_b32_e32 v3, s0, v2
	v_writelane_b32 v255, s11, 16
	s_cselect_b64 s[10:11], -1, 0
	v_writelane_b32 v254, s10, 61
	s_cmp_gt_u32 s2, 33
	v_add_u32_e32 v176, s1, v90
	v_writelane_b32 v254, s11, 62
	s_cselect_b64 s[10:11], -1, 0
	s_lshl_b32 s70, s2, 10
	s_ashr_i32 s2, s70, 31
	v_writelane_b32 v255, s10, 19
	s_cmp_gt_i32 s4, -8
	v_add_u32_e32 v127, s5, v90
	v_writelane_b32 v255, s11, 20
	s_cselect_b64 s[10:11], -1, 0
	v_writelane_b32 v254, s10, 59
	s_cmp_gt_u32 s13, 33
	v_writelane_b32 v255, s2, 22
	v_writelane_b32 v254, s11, 60
	s_cselect_b64 s[10:11], -1, 0
	s_lshl_b32 s96, s13, 10
	s_ashr_i32 s2, s96, 31
	v_writelane_b32 v255, s10, 25
	s_cmp_gt_i32 s4, -16
	v_mul_lo_u32 v174, v3, s71
	v_writelane_b32 v255, s11, 26
	s_cselect_b64 s[10:11], -1, 0
	v_writelane_b32 v255, s2, 28
	v_writelane_b32 v254, s10, 63
	s_cmp_gt_u32 s14, 33
	v_or3_b32 v3, v2, s8, 48
	v_writelane_b32 v255, s11, 0
	s_cselect_b64 s[10:11], -1, 0
	s_lshl_b32 s97, s14, 10
	s_ashr_i32 s2, s97, 31
	v_writelane_b32 v255, s10, 31
	s_cmpk_gt_i32 s4, 0xffe8
	v_mul_u32_u24_e32 v128, 0x110, v2
	v_writelane_b32 v255, s11, 32
	s_cselect_b64 s[10:11], -1, 0
	v_writelane_b32 v254, s10, 57
	s_cmp_gt_u32 s15, 33
	v_writelane_b32 v255, s2, 34
	v_writelane_b32 v254, s11, 58
	s_cselect_b64 s[10:11], -1, 0
	s_lshl_b32 s12, s15, 10
	s_ashr_i32 s2, s12, 31
	v_writelane_b32 v255, s10, 42
	s_cmpk_gt_i32 s4, 0xffe0
	s_waitcnt vmcnt(0)
	v_mul_lo_u32 v175, v3, s71
	v_writelane_b32 v255, s11, 43
	s_cselect_b64 s[10:11], -1, 0
	v_writelane_b32 v254, s10, 34
	s_cmp_gt_u32 s16, 33
	v_writelane_b32 v255, s2, 14
	v_writelane_b32 v254, s11, 35
	s_cselect_b64 s[10:11], -1, 0
	s_lshl_b32 s13, s16, 10
	s_ashr_i32 s2, s13, 31
	v_writelane_b32 v255, s10, 17
	s_cmpk_gt_i32 s4, 0xffd8
	v_mov_b32_e32 v3, v11
	v_writelane_b32 v255, s11, 18
	s_cselect_b64 s[10:11], -1, 0
	v_writelane_b32 v254, s10, 40
	s_cmp_gt_u32 s3, 33
	v_writelane_b32 v255, s2, 21
	v_writelane_b32 v254, s11, 41
	s_cselect_b64 s[10:11], -1, 0
	s_lshl_b32 s28, s3, 10
	v_writelane_b32 v255, s10, 23
	s_ashr_i32 s2, s28, 31
	s_cmpk_gt_i32 s4, 0xffd0
	v_writelane_b32 v255, s11, 24
	v_writelane_b32 v255, s2, 27
	s_cselect_b64 s[2:3], -1, 0
	v_writelane_b32 v254, s2, 42
	s_cmp_gt_u32 s6, 33
	v_lshlrev_b32_e32 v4, 1, v126
	v_writelane_b32 v254, s3, 43
	s_cselect_b64 s[2:3], -1, 0
	v_writelane_b32 v255, s2, 29
	s_lshl_b32 s29, s6, 10
	v_mov_b32_e32 v5, v11
	v_writelane_b32 v255, s3, 30
	s_ashr_i32 s2, s29, 31
	s_cmp_gt_u32 s4, 3
	s_cselect_b64 s[40:41], -1, 0
	s_and_b64 s[0:1], s[40:41], exec
	s_cselect_b32 s0, 4, 0
	s_cselect_b32 s1, 16, 0
	v_readlane_b32 s3, v251, 46
	v_or_b32_e32 v177, s1, v2
	s_cselect_b32 s1, 2, 3
	s_or_b32 s0, s0, s3
	s_lshr_b32 s0, 0x65217430, s0
	v_writelane_b32 v255, s2, 33
	s_and_b32 s2, s0, 3
	s_lshl_b32 s18, s2, 4
	s_xor_b32 s0, s35, 0x2000
	s_cmp_gt_u32 s2, 1
	v_add_u32_e32 v178, s0, v127
	s_cselect_b64 s[10:11], -1, 0
	s_lshl_b32 s0, s1, 2
	s_or_b32 s0, s0, s3
	s_lshr_b32 s0, 0x65217430, s0
	s_and_b32 s3, s0, 7
	s_lshl_b32 s19, s3, 4
	s_cmp_gt_u32 s3, 5
	v_lshl_or_b32 v179, s1, 4, v2
	s_cselect_b64 s[16:17], -1, 0
	s_add_i32 s1, 0, 0x22000
	s_add_i32 s8, s33, 0
	s_add_i32 s9, s25, 0
	s_add_i32 s84, s70, 0
	s_add_i32 s85, s96, 0
	s_add_i32 s68, s97, 0
	s_add_i32 s69, s12, 0
	s_add_i32 s14, s13, 0
	s_add_i32 s15, s28, 0
	s_add_i32 s0, s29, 0
	v_lshl_add_u32 v180, v150, 2, s1
	s_lshl_b32 s1, s3, 16
	s_lshl_b32 s4, s2, 16
	v_readlane_b32 s2, v252, 51
	s_add_u32 s2, s31, s2
	v_readlane_b32 s3, v252, 52
	s_addc_u32 s3, s30, s3
	s_add_u32 s5, s2, s33
	v_writelane_b32 v255, s5, 7
	s_addc_u32 s5, s3, 0
	v_writelane_b32 v255, s5, 8
	s_add_u32 s5, s2, s25
	v_writelane_b32 v255, s5, 9
	s_addc_u32 s5, s3, 0
	v_writelane_b32 v255, s5, 10
	s_add_u32 s5, s2, s70
	v_writelane_b32 v255, s5, 11
	s_addc_u32 s5, s3, 0
	v_writelane_b32 v255, s5, 12
	s_add_u32 s5, s2, s96
	v_writelane_b32 v255, s5, 1
	s_addc_u32 s5, s3, 0
	v_writelane_b32 v255, s5, 2
	s_add_u32 s5, s2, s97
	v_writelane_b32 v255, s5, 3
	s_addc_u32 s5, s3, 0
	v_writelane_b32 v255, s5, 4
	s_add_u32 s5, s2, s12
	v_writelane_b32 v255, s5, 5
	s_addc_u32 s5, s3, 0
	v_writelane_b32 v255, s5, 6
	s_add_u32 s5, s2, s13
	v_writelane_b32 v255, s5, 35
	s_addc_u32 s5, s3, 0
	v_writelane_b32 v255, s5, 36
	s_add_u32 s5, s2, s28
	v_writelane_b32 v255, s5, 37
	s_addc_u32 s5, s3, 0
	v_writelane_b32 v255, s5, 38
	s_add_u32 s2, s2, s29
	v_writelane_b32 v255, s2, 39
	s_addc_u32 s2, s3, 0
	v_writelane_b32 v255, s2, 40
	v_readlane_b32 s2, v252, 54
	v_and_b32_e32 v2, 48, v150
	s_add_u32 s2, s31, s2
	v_readlane_b32 s3, v252, 55
	v_lshrrev_b32_e32 v2, 1, v2
	s_addc_u32 s3, s30, s3
	v_lshl_add_u64 v[2:3], v[2:3], 0, v[4:5]
	v_mov_b32_e32 v28, 0
	s_mov_b32 s76, 0
	v_or_b32_e32 v129, 1, v115
	v_or_b32_e32 v130, 2, v115
	v_or_b32_e32 v131, 3, v115
	v_or_b32_e32 v132, 16, v115
	v_or_b32_e32 v133, 17, v115
	v_or_b32_e32 v134, 18, v115
	v_or_b32_e32 v135, 19, v115
	v_or_b32_e32 v136, 32, v115
	v_or_b32_e32 v137, 33, v115
	v_or_b32_e32 v138, 34, v115
	v_or_b32_e32 v139, 35, v115
	v_or_b32_e32 v140, 48, v115
	v_or_b32_e32 v141, 49, v115
	v_or_b32_e32 v142, 50, v115
	v_or_b32_e32 v143, 51, v115
	v_or_b32_e32 v144, 64, v115
	v_or_b32_e32 v145, 0x41, v115
	v_or_b32_e32 v146, 0x42, v115
	v_or_b32_e32 v147, 0x43, v115
	v_or_b32_e32 v148, 0x50, v115
	v_or_b32_e32 v149, 0x51, v115
	v_or_b32_e32 v151, 0x52, v115
	v_or_b32_e32 v161, 0x53, v115
	v_or_b32_e32 v166, 0x60, v115
	v_or_b32_e32 v167, 0x61, v115
	v_or_b32_e32 v168, 0x62, v115
	v_or_b32_e32 v169, 0x63, v115
	v_or_b32_e32 v170, 0x70, v115
	v_or_b32_e32 v171, 0x71, v115
	v_or_b32_e32 v172, 0x72, v115
	v_or_b32_e32 v173, 0x73, v115
	v_add_u32_e32 v94, 0x80, v150
	v_lshl_add_u64 v[96:97], s[2:3], 0, v[2:3]
	s_mov_b64 s[94:95], 0
	v_mov_b32_e32 v29, v28
	v_mov_b32_e32 v30, v28
	v_mov_b32_e32 v31, v28
	v_mov_b32_e32 v32, v28
	v_mov_b32_e32 v33, v28
	v_mov_b32_e32 v34, v28
	v_mov_b32_e32 v35, v28
	v_mov_b32_e32 v36, v28
	v_mov_b32_e32 v37, v28
	v_mov_b32_e32 v38, v28
	v_mov_b32_e32 v39, v28
	v_mov_b32_e32 v40, v28
	v_mov_b32_e32 v41, v28
	v_mov_b32_e32 v42, v28
	v_mov_b32_e32 v43, v28
	s_waitcnt vmcnt(0) lgkmcnt(0)
	s_barrier
	v_readlane_b32 s62, v250, 8
	s_and_b32 s62, s62, 3
	s_lshr_b32 s63, s62, 1
	s_and_b32 s62, s62, 1
	s_lshl_b32 s53, s63, 6
	s_lshl_b32 s54, s62, 5
	s_add_i32 s53, s53, s54
	s_lshl_b32 s54, s53, 1
	s_branch .LBB0_1650

.LBB0_1744:
	s_and_saveexec_b64 s[50:51], s[38:39]
	s_lshl_b32 s52, s5, 10
	v_add_u32_e32 v188, s52, v180
	s_add_i32 s52, s52, 0x221fc
	v_mov_b32_e32 v189, s52
	ds_read_b32 v190, v188
	ds_read_b32 v191, v189
	s_waitcnt lgkmcnt(0)
	v_sub_f32_e32 v190, v191, v190
	v_exp_f32_e32 v190, v190
	v_add_u32_e32 v188, 0x4800, v180
	s_nop 0
	ds_write_b32 v188, v190
	s_or_b64 exec, exec, s[50:51]
	s_mul_i32 s2, s5, 0x11000
	s_add_i32 s2, s2, 0
	s_add_i32 s3, s23, s2
	v_add3_u32 v10, s3, v128, v88
	v_add_u32_e32 v44, 0x4000, v10
	v_cvt_pk_bf16_f32 v2, v28, v29
	v_cvt_pk_bf16_f32 v3, v30, v31
	v_cvt_pk_bf16_f32 v4, v32, v33
	v_cvt_pk_bf16_f32 v5, v34, v35
	ds_read2_b64 v[6:9], v44 offset0:128 offset1:132
	v_cvt_pk_bf16_f32 v48, v36, v37
	v_cvt_pk_bf16_f32 v49, v38, v39
	v_cvt_pk_bf16_f32 v50, v40, v41
	v_cvt_pk_bf16_f32 v51, v42, v43
	ds_read2_b64 v[44:47], v44 offset0:136 offset1:140
	s_waitcnt lgkmcnt(0)
	v_mfma_f32_16x16x32_bf16 v[6:9], v[2:5], v[6:9], 0
	s_lshl_b32 s5, s5, 10
	s_add_i32 s65, s5, 0
	s_add_i32 s65, s65, 0x22000
	v_mfma_f32_16x16x32_bf16 v[52:55], v[48:51], v[44:47], v[6:9]
	v_add_u32_e32 v44, 0x5000, v10
	v_add_u32_e32 v114, s2, v88
	v_lshl_add_u32 v182, v115, 2, s65
	v_mul_u32_u24_e32 v188, 0x110, v179
	v_add3_u32 v188, v188, v114, s53
	v_and_b32_e32 v189, 15, v179
	v_or_b32_e32 v189, s19, v189
	v_lshl_add_u32 v189, v189, 2, s65
	v_add_u32_e32 v193, s54, v182
	ds_read_b64 v[200:201], v188
	ds_read_b32 v192, v189
	ds_read_b128 v[202:205], v193
	s_waitcnt lgkmcnt(0)
	v_sub_f32_e32 v202, v192, v202
	v_sub_f32_e32 v203, v192, v203
	v_sub_f32_e32 v204, v192, v204
	v_sub_f32_e32 v205, v192, v205
	v_exp_f32_e32 v202, v202
	v_exp_f32_e32 v203, v203
	v_exp_f32_e32 v204, v204
	v_exp_f32_e32 v205, v205
	v_lshlrev_b32_e32 v190, 16, v200
	v_and_b32_e32 v191, 0xffff0000, v200
	v_pk_mul_f32 v[202:203], v[202:203], v[190:191]
	v_lshlrev_b32_e32 v190, 16, v201
	v_and_b32_e32 v191, 0xffff0000, v201
	v_pk_mul_f32 v[204:205], v[204:205], v[190:191]
	s_nop 0
	v_cvt_pk_bf16_f32 v200, v202, v203
	v_cvt_pk_bf16_f32 v201, v204, v205
	s_nop 0
	ds_write_b64 v188, v[200:201]
	s_nop 0
	ds_read2_b64 v[6:9], v44 offset0:160 offset1:164
	ds_read2_b64 v[44:47], v44 offset0:168 offset1:172
	s_waitcnt lgkmcnt(0)
	v_mfma_f32_16x16x32_bf16 v[6:9], v[2:5], v[6:9], 0
	s_mov_b64 s[42:43], -1
	s_andn2_b64 vcc, exec, s[10:11]
	v_mfma_f32_16x16x32_bf16 v[56:59], v[48:51], v[44:47], v[6:9]
	v_add_u32_e32 v44, 0x6000, v10
	v_add_u32_e32 v10, 0x7000, v10
	ds_read2_b64 v[60:63], v10 offset0:224 offset1:228
	s_nop 1
	ds_read2_b64 v[6:9], v44 offset0:192 offset1:196
	ds_read2_b64 v[44:47], v44 offset0:200 offset1:204
	s_waitcnt lgkmcnt(0)
	v_mfma_f32_16x16x32_bf16 v[6:9], v[2:5], v[6:9], 0
	v_mfma_f32_16x16x32_bf16 v[44:47], v[48:51], v[44:47], v[6:9]
	s_nop 6
	ds_read2_b64 v[6:9], v10 offset0:232 offset1:236
	v_mfma_f32_16x16x32_bf16 v[2:5], v[2:5], v[60:63], 0
	v_mov_b32_e32 v10, s65
	ds_read_b32 v181, v10 offset:508
	s_waitcnt lgkmcnt(0)
	v_mfma_f32_16x16x32_bf16 v[48:51], v[48:51], v[6:9], v[2:5]
	v_add_u32_e32 v6, s35, v127
	s_nop 2
	v_cndmask_b32_e64 v5, v59, v55, s[40:41]
	v_cndmask_b32_e64 v4, v58, v54, s[40:41]
	v_cndmask_b32_e64 v3, v57, v53, s[40:41]
	v_cndmask_b32_e64 v2, v56, v52, s[40:41]
	ds_write_b128 v6, v[2:5]
	v_cndmask_b32_e64 v5, v47, v51, s[40:41]
	v_cndmask_b32_e64 v4, v46, v50, s[40:41]
	v_cndmask_b32_e64 v3, v45, v49, s[40:41]
	v_cndmask_b32_e64 v2, v44, v48, s[40:41]
	ds_write_b128 v176, v[2:5] offset:1024
	v_mov_b32_e32 v2, v177
	s_waitcnt lgkmcnt(0)
	s_barrier
	s_nop 0
	v_and_b32_e32 v10, 15, v2
	v_or_b32_e32 v86, s18, v10
	v_lshl_add_u32 v3, v86, 2, s65
	v_mad_u64_u32 v[6:7], s[2:3], v2, s71, v[114:115]
	ds_read2st64_b32 v[76:77], v3 offset1:2
	ds_read2_b64 v[2:5], v6 offset1:4
	ds_read2_b64 v[64:67], v6 offset0:8 offset1:12
	ds_read_b128 v[60:63], v178
	ds_read_b128 v[72:75], v182
	ds_read_b128 v[68:71], v182 offset:64
	s_waitcnt lgkmcnt(0)
	v_lshlrev_b32_e32 v84, 16, v2
	v_and_b32_e32 v85, 0xffff0000, v2
	v_lshlrev_b32_e32 v82, 16, v3
	v_and_b32_e32 v83, 0xffff0000, v3
	v_lshlrev_b32_e32 v80, 16, v4
	v_and_b32_e32 v81, 0xffff0000, v4
	v_lshlrev_b32_e32 v78, 16, v5
	v_and_b32_e32 v79, 0xffff0000, v5
	s_cbranch_vccnz .LBB0_1746
	v_sub_f32_e32 v2, v76, v72
	v_sub_f32_e32 v3, v76, v73
	v_sub_f32_e32 v4, v76, v74
	v_sub_f32_e32 v5, v76, v75
	v_sub_f32_e32 v6, v76, v68
	v_sub_f32_e32 v7, v76, v69
	v_sub_f32_e32 v8, v76, v70
	v_sub_f32_e32 v9, v76, v71
	v_exp_f32_e32 v2, v2
	v_exp_f32_e32 v3, v3
	v_exp_f32_e32 v4, v4
	v_exp_f32_e32 v5, v5
	v_exp_f32_e32 v6, v6
	v_exp_f32_e32 v8, v8
	v_exp_f32_e32 v9, v9
	v_exp_f32_e32 v7, v7
	v_pk_mul_f32 v[2:3], v[2:3], v[84:85]
	v_pk_mul_f32 v[4:5], v[4:5], v[82:83]
	v_pk_mul_f32 v[8:9], v[8:9], v[78:79]
	v_pk_mul_f32 v[6:7], v[6:7], v[80:81]
	s_mov_b64 s[42:43], 0

.LBB0_1816:
	s_nop 1
	v_cndmask_b32_e64 v2, v54, v58, s[40:41]
	v_exp_f32_e32 v54, v76
	v_cndmask_b32_e64 v3, v55, v59, s[40:41]
	v_cndmask_b32_e64 v5, v53, v57, s[40:41]
	v_cndmask_b32_e64 v4, v52, v56, s[40:41]
	v_pk_add_f32 v[4:5], v[4:5], v[60:61]
	v_pk_add_f32 v[2:3], v[2:3], v[62:63]
	v_pk_fma_f32 v[4:5], v[54:55], v[4:5], v[6:7] op_sel_hi:[0,1,1]
	v_pk_fma_f32 v[2:3], v[54:55], v[2:3], v[8:9] op_sel_hi:[0,1,1]
	v_lshl_add_u32 v10, v10, 12, s4
	v_cvt_pk_bf16_f32 v4, v4, v5
	v_cvt_pk_bf16_f32 v5, v2, v3
	v_lshl_add_u64 v[2:3], v[10:11], 1, v[92:93]
	global_store_dwordx2 v[2:3], v[4:5], off
	v_mov_b32_e32 v2, v179
	s_mov_b64 s[72:73], -1
	v_and_b32_e32 v10, 15, v2
	v_or_b32_e32 v183, s19, v10
	v_lshl_add_u32 v3, v183, 2, s65
	ds_read2st64_b32 v[116:117], v3 offset1:2
	v_mad_u64_u32 v[52:53], s[2:3], v2, s71, v[114:115]
	ds_read2_b64 v[2:5], v52 offset1:4
	ds_read_b128 v[76:79], v178 offset:1024
	ds_read2_b64 v[6:9], v52 offset0:8 offset1:12
	ds_read2_b64 v[184:187], v52 offset0:16 offset1:20
	ds_read2_b64 v[80:83], v52 offset0:24 offset1:28
	s_waitcnt lgkmcnt(0)
	s_waitcnt lgkmcnt(0)
	v_mfma_f32_16x16x32_bf16 v[2:5], v[24:27], v[2:5], 0
	ds_read_b128 v[64:67], v182 offset:256
	ds_read_b128 v[52:55], v182 offset:320
	v_lshlrev_b32_e32 v124, 16, v184
	v_mfma_f32_16x16x32_bf16 v[84:87], v[20:23], v[6:9], v[2:5]
	s_andn2_b64 vcc, exec, s[16:17]
	v_and_b32_e32 v125, 0xffff0000, v184
	v_lshlrev_b32_e32 v122, 16, v185
	v_cndmask_b32_e64 v2, 0, 1, s[16:17]
	v_cmp_ne_u32_e64 s[42:43], 1, v2
	v_and_b32_e32 v123, 0xffff0000, v185
	v_lshlrev_b32_e32 v120, 16, v186
	v_and_b32_e32 v121, 0xffff0000, v186
	v_lshlrev_b32_e32 v118, 16, v187
	v_and_b32_e32 v119, 0xffff0000, v187
	s_cbranch_vccnz .LBB0_1818
	s_waitcnt lgkmcnt(0)
	v_sub_f32_e32 v2, v116, v64
	v_sub_f32_e32 v3, v116, v65
	v_sub_f32_e32 v4, v116, v66
	v_sub_f32_e32 v5, v116, v67
	v_sub_f32_e32 v6, v116, v52
	v_sub_f32_e32 v7, v116, v53
	v_sub_f32_e32 v8, v116, v54
	v_sub_f32_e32 v9, v116, v55
	v_exp_f32_e32 v2, v2
	v_exp_f32_e32 v3, v3
	v_exp_f32_e32 v4, v4
	v_exp_f32_e32 v5, v5
	v_exp_f32_e32 v6, v6
	v_exp_f32_e32 v8, v8
	v_exp_f32_e32 v9, v9
	v_exp_f32_e32 v7, v7
	v_pk_mul_f32 v[2:3], v[2:3], v[124:125]
	v_pk_mul_f32 v[4:5], v[4:5], v[122:123]
	v_pk_mul_f32 v[8:9], v[8:9], v[118:119]
	v_pk_mul_f32 v[6:7], v[6:7], v[120:121]
	s_mov_b64 s[72:73], 0

.LBB0_1888:
	s_nop 0
	s_nop 0
	s_nop 0
	s_nop 0
	s_nop 0
	s_nop 0
	s_nop 0
	s_nop 0
	s_nop 0
	s_nop 0
	s_nop 0
	s_nop 0
	s_nop 0
	s_nop 0
	s_nop 0
	s_nop 0
	s_nop 0
	s_nop 0
	s_nop 0
	s_nop 0
	s_nop 0
	s_nop 0
	s_nop 0
	s_nop 0
	s_nop 0
	s_nop 0
	s_nop 0
	s_nop 0
	s_nop 0
	s_nop 0
	s_nop 0
	s_nop 0
	s_nop 0
	s_nop 0
	s_nop 0
	s_nop 0
	s_nop 0
	s_nop 0
	s_nop 0
	s_nop 0
	s_nop 0
	s_nop 0
	s_nop 0
	s_nop 0
	s_nop 0
	s_nop 0
	s_nop 0
	v_readlane_b32 s0, v251, 47
	v_readlane_b32 s1, v251, 48
	s_and_b64 vcc, exec, s[0:1]
	s_cbranch_vccz .LBB0_1890
	v_readlane_b32 s0, v254, 0
	v_lshlrev_b32_e32 v4, 2, v115
	v_mov_b32_e32 v5, v11
	v_mov_b32_e32 v1, s0
	ds_read_b64 v[2:3], v1
	v_readlane_b32 s0, v251, 36
	s_add_i32 s0, s79, s0
	s_ashr_i32 s1, s0, 31
	s_lshl_b64 s[0:1], s[0:1], 21
	s_waitcnt lgkmcnt(0)
	v_readfirstlane_b32 s3, v2
	v_readfirstlane_b32 s2, v3
	s_add_u32 s0, s3, s0
	s_addc_u32 s1, s2, s1
	v_readlane_b32 s2, v253, 23
	s_add_u32 s0, s0, s2
	s_addc_u32 s1, s1, 0
	v_lshlrev_b32_e32 v2, 2, v126
	v_mov_b32_e32 v3, v11
	v_lshl_add_u64 v[2:3], s[0:1], 0, v[2:3]
	s_lshl_b32 s0, s45, 6
	s_ashr_i32 s1, s0, 31
	v_lshl_add_u64 v[2:3], s[0:1], 2, v[2:3]
	v_lshl_add_u64 v[2:3], v[2:3], 0, v[4:5]
	s_mov_b64 s[0:1], 0x4364000
	v_lshl_add_u64 v[4:5], v[2:3], 0, s[0:1]
	v_add_co_u32_e32 v2, vcc, 0x4364000, v2
	s_nop 1
	v_addc_co_u32_e32 v3, vcc, 0, v3, vcc
	global_store_dwordx4 v[2:3], v[28:31], off
	global_store_dwordx4 v[4:5], v[32:35], off offset:64
	global_store_dwordx4 v[4:5], v[36:39], off offset:128
	global_store_dwordx4 v[4:5], v[40:43], off offset:192
